# all K-fragment pairs except the first issued just-in-time (need-ordered) in all four QK segments
# speedup vs baseline: 1.0106x; 1.0106x over previous
; #define SBAR() __builtin_amdgcn_sched_barrier(0)
; #define KWRITE(b, src0, src1) do { if constexpr (ND0 == 4) { *(bf16x8*)(K_lds + (b) * SHM_K + KSWZ(kr, kcb)) = src0; } \
;     else { int kc = sc * 2; *(bf16x8*)(K_lds + (b) * SHM_K + KSWZ(sr, kc)) = src0; *(bf16x8*)(K_lds + (b) * SHM_K + KSWZ(32 + sr, kc)) = src1; } } while (0)
; #define SLOAD_B(k0) do { vs0b = *reinterpret_cast<const bf16x8*>(&Vh[(long)((k0) + sr) * LDK + sc]); vs1b = *reinterpret_cast<const bf16x8*>(&Vh[(long)((k0) + 32 + sr) * LDK + sc]); KLOAD(ks0b, ks1b, k0); } while (0)
; #define PSM(P0, P1, MN, AL) do { if constexpr (PRE) partialSM_pre(P0, P1, m_reg, AL, 11.541560327111707f); else partialSM(P0, P1, m_reg, MN, AL, C, thr_raw); } while (0)
; __device__ __forceinline__ void finishSM(f32x16& p0, f32x16& p1, float alpha, float& l_reg, bf16x8& pa0, bf16x8& pa1, bf16x8& pa2, bf16x8& pa3) {
; #pragma unroll
;   for (int r = 0; r < 16; ++r) p1[r] = __builtin_amdgcn_exp2f(p1[r]);
;   float ps = 0;
; #pragma unroll
;   for (int r = 0; r < 16; ++r) ps += p0[r];
; #pragma unroll
;   for (int r = 0; r < 16; ++r) ps += p1[r];
;   { auto rr = __builtin_amdgcn_permlane32_swap(__float_as_uint(ps), __float_as_uint(ps), false, false);
;     ps = __uint_as_float(rr[0]) + __uint_as_float(rr[1]); }
;   l_reg = l_reg * alpha + ps;
;     ...
;   PK4(p0, 0, pa0); PK4(p0, 8, pa1); PK4(p1, 0, pa2); PK4(p1, 8, pa3);
;     ...
; }
; template <int ND0>
; __device__ __forceinline__ void qkt(f32x16& p0, f32x16& p1, const char* Ks, const bf16x8* qr, int r32, int hi) {
;   p0 = f32x16{}; p1 = f32x16{};
; #pragma unroll
;   for (int d0 = 0; d0 < ND0; ++d0) { int cb = (d0 * 16 + hi * 8) * 2;
;     bf16x8 b0 = *reinterpret_cast<const bf16x8*>(Ks + KSWZ(r32, cb));
;     bf16x8 b1 = *reinterpret_cast<const bf16x8*>(Ks + KSWZ(32 + r32, cb));
;     p0 = __builtin_amdgcn_mfma_f32_32x32x16_bf16(b0, qr[d0], p0, 0, 0, 0);
;     p1 = __builtin_amdgcn_mfma_f32_32x32x16_bf16(b1, qr[d0], p1, 0, 0, 0); }
; }
; template <int ND0, int LDQ, int LDK, int LDO> ...
;     ...
;     SBAR(); qkt<ND0>(pB0, pB1, Kq1, qr, r32, hi);
;     finishSM(pA0, pA1, alA, l_reg, pa0, pa1, pa2, pa3); SBAR();
;     SLOAD_B((j + 2) * KVBLK); SBAR();
;     pv_d0(o, vb0, pa0, pa1, pa2, pa3); KWRITE(0, ks0a, ks1a); PSM(pB0, pB1, mnB, alB);
.LBB0_146:
	v_exp_f32_e32 v170, v64
	s_waitcnt lgkmcnt(0)
	v_mfma_f32_32x32x16_bf16 v[96:111], v[80:83], v[114:117], 0
	v_add_f32_e32 v64, v213, v176
	v_add_f32_e32 v64, v174, v64
	v_add_f32_e32 v64, v177, v64
	v_add_f32_e32 v64, v173, v64
	v_add_f32_e32 v64, v175, v64
	v_add_f32_e32 v64, v171, v64
	v_add_f32_e32 v64, v172, v64
	v_mfma_f32_32x32x16_bf16 v[80:95], v[84:87], v[114:117], 0
	ds_read_b128 v[208:211], v200 offset:49152
	ds_read_b128 v[214:217], v200 offset:57344
	v_add_f32_e32 v64, v167, v64
	v_add_f32_e32 v64, v169, v64
	v_add_f32_e32 v64, v166, v64
	v_add_f32_e32 v64, v168, v64
	v_add_f32_e32 v64, v163, v64
	v_add_f32_e32 v64, v165, v64
	v_add_f32_e32 v64, v162, v64
	s_waitcnt lgkmcnt(0)
	v_mfma_f32_32x32x16_bf16 v[96:111], v[208:211], v[122:125], v[96:111]
	v_exp_f32_e32 v212, v67
	v_add_f32_e32 v64, v164, v64
	v_add_f32_e32 v64, v170, v64
	v_exp_f32_e32 v218, v72
	v_exp_f32_e32 v219, v73
	v_exp_f32_e32 v220, v74
	v_exp_f32_e32 v221, v75
	v_mfma_f32_32x32x16_bf16 v[80:95], v[214:217], v[122:125], v[80:95]
	ds_read_b128 v[208:211], v202 offset:49152
	ds_read_b128 v[214:217], v202 offset:57344
	v_exp_f32_e32 v222, v76
	v_exp_f32_e32 v223, v77
	v_exp_f32_e32 v224, v78
	v_exp_f32_e32 v79, v79
	s_waitcnt lgkmcnt(0)
	v_mfma_f32_32x32x16_bf16 v[96:111], v[208:211], v[142:145], v[96:111]
	v_mfma_f32_32x32x16_bf16 v[80:95], v[214:217], v[142:145], v[80:95]
	ds_read_b128 v[208:211], v201 offset:49152
	ds_read_b128 v[214:217], v201 offset:57344
	s_waitcnt lgkmcnt(0)
	v_mfma_f32_32x32x16_bf16 v[96:111], v[208:211], v[138:141], v[96:111]
	v_mfma_f32_32x32x16_bf16 v[80:95], v[214:217], v[138:141], v[80:95]
	ds_read_b128 v[208:211], v203 offset:49152
	ds_read_b128 v[214:217], v203 offset:57344
	s_waitcnt lgkmcnt(0)
	v_mfma_f32_32x32x16_bf16 v[96:111], v[208:211], v[134:137], v[96:111]
	v_mfma_f32_32x32x16_bf16 v[80:95], v[214:217], v[134:137], v[80:95]
	ds_read_b128 v[208:211], v204 offset:49152
	ds_read_b128 v[214:217], v204 offset:57344
	s_waitcnt lgkmcnt(0)
	v_mfma_f32_32x32x16_bf16 v[96:111], v[208:211], v[130:133], v[96:111]
	v_mfma_f32_32x32x16_bf16 v[80:95], v[214:217], v[130:133], v[80:95]
	ds_read_b128 v[208:211], v206 offset:49152
	ds_read_b128 v[214:217], v206 offset:57344
	s_waitcnt lgkmcnt(0)
	v_mfma_f32_32x32x16_bf16 v[96:111], v[208:211], v[126:129], v[96:111]
	v_mfma_f32_32x32x16_bf16 v[80:95], v[214:217], v[126:129], v[80:95]
	ds_read_b128 v[208:211], v205 offset:49152
	ds_read_b128 v[214:217], v205 offset:57344
	s_waitcnt lgkmcnt(0)
	v_mfma_f32_32x32x16_bf16 v[96:111], v[208:211], v[118:121], v[96:111]
	v_exp_f32_e32 v210, v65
	v_exp_f32_e32 v211, v66
	v_add_f32_e32 v64, v210, v64
	v_add_f32_e32 v64, v211, v64
	v_add_f32_e32 v64, v212, v64
	v_mfma_f32_32x32x16_bf16 v[80:95], v[214:217], v[118:121], v[80:95]
	v_exp_f32_e32 v214, v68
	v_exp_f32_e32 v215, v69
	v_exp_f32_e32 v216, v70
	v_exp_f32_e32 v217, v71
	v_add_f32_e32 v64, v214, v64
	v_add_f32_e32 v64, v215, v64
	v_add_f32_e32 v64, v216, v64
	v_add_f32_e32 v64, v217, v64
	v_add_f32_e32 v64, v218, v64
	v_add_f32_e32 v64, v219, v64
	v_add_f32_e32 v64, v220, v64
	v_add_f32_e32 v64, v221, v64
	v_add_f32_e32 v64, v222, v64
	v_add_f32_e32 v64, v223, v64
	v_add_f32_e32 v64, v224, v64
	v_add_f32_e32 v208, v79, v64
	v_mov_b32_e32 v209, v208
	v_cvt_pk_bf16_f32 v64, v176, v213
	v_cvt_pk_bf16_f32 v65, v174, v177
	v_cvt_pk_bf16_f32 v66, v173, v175
	v_cvt_pk_bf16_f32 v67, v171, v172
	v_cvt_pk_bf16_f32 v68, v167, v169
	v_cvt_pk_bf16_f32 v69, v166, v168
	v_cvt_pk_bf16_f32 v70, v163, v165
	v_cvt_pk_bf16_f32 v71, v162, v164
	v_cvt_pk_bf16_f32 v72, v170, v210
	v_cvt_pk_bf16_f32 v73, v211, v212
	v_cvt_pk_bf16_f32 v74, v214, v215
	v_cvt_pk_bf16_f32 v75, v216, v217
	v_cvt_pk_bf16_f32 v76, v218, v219
	v_cvt_pk_bf16_f32 v77, v220, v221
	v_cvt_pk_bf16_f32 v78, v222, v223
	v_cvt_pk_bf16_f32 v79, v224, v79
	v_permlane32_swap_b32_e32 v208, v209
	v_permlane32_swap_b32_e32 v64, v66
	v_permlane32_swap_b32_e32 v65, v67
	v_permlane32_swap_b32_e32 v68, v70
	v_permlane32_swap_b32_e32 v69, v71
	v_permlane32_swap_b32_e32 v72, v74
	v_permlane32_swap_b32_e32 v73, v75
	v_permlane32_swap_b32_e32 v76, v78
	v_permlane32_swap_b32_e32 v77, v79
	s_mov_b32 s4, 0xfffb8000
	v_add_co_u32_e32 v166, vcc, s4, v188
	s_mov_b32 s4, 0xfffd0000
	s_nop 0
	v_addc_co_u32_e32 v167, vcc, -1, v189, vcc
	v_add_co_u32_e32 v174, vcc, s4, v188
	s_nop 1
	v_addc_co_u32_e32 v175, vcc, -1, v189, vcc
	global_load_dwordx4 v[162:165], v[166:167], off
	global_load_dwordx4 v[170:173], v[166:167], off offset:-512
	global_load_dwordx4 v[166:169], v[174:175], off
	global_load_dwordx4 v[174:177], v[174:175], off offset:-512
	v_cmp_neq_f32_e32 vcc, 0, v193
	ds_read_b64_tr_b16 v[210:211], v194 offset:0
	ds_read_b64_tr_b16 v[212:213], v194 offset:0x800
	ds_read_b64_tr_b16 v[214:215], v194 offset:0x1000
	ds_read_b64_tr_b16 v[216:217], v194 offset:0x1800
	ds_read_b64_tr_b16 v[218:219], v194 offset:0x2000
	ds_read_b64_tr_b16 v[220:221], v194 offset:0x2800
	ds_read_b64_tr_b16 v[222:223], v194 offset:0x3000
	ds_read_b64_tr_b16 v[224:225], v194 offset:0x3800
	s_cbranch_vccnz .LBB0_163

; #define SBAR() __builtin_amdgcn_sched_barrier(0)
; #define SLOAD_A(k0) do { vs0a = *reinterpret_cast<const bf16x8*>(&Vh[(long)((k0) + sr) * LDK + sc]); vs1a = *reinterpret_cast<const bf16x8*>(&Vh[(long)((k0) + 32 + sr) * LDK + sc]); KLOAD(ks0a, ks1a, k0); } while (0)
; __device__ __forceinline__ void finishSM(f32x16& p0, f32x16& p1, float alpha, float& l_reg, bf16x8& pa0, bf16x8& pa1, bf16x8& pa2, bf16x8& pa3) {
; #pragma unroll
;   for (int r = 0; r < 16; ++r) p1[r] = __builtin_amdgcn_exp2f(p1[r]);
;   float ps = 0;
; #pragma unroll
;   for (int r = 0; r < 16; ++r) ps += p0[r];
; #pragma unroll
;   for (int r = 0; r < 16; ++r) ps += p1[r];
;   { auto rr = __builtin_amdgcn_permlane32_swap(__float_as_uint(ps), __float_as_uint(ps), false, false);
;     ps = __uint_as_float(rr[0]) + __uint_as_float(rr[1]); }
;   l_reg = l_reg * alpha + ps;
;     ...
;   PK4(p0, 0, pa0); PK4(p0, 8, pa1); PK4(p1, 0, pa2); PK4(p1, 8, pa3);
;     ...
; }
; template <int ND0>
; __device__ __forceinline__ void qkt(f32x16& p0, f32x16& p1, const char* Ks, const bf16x8* qr, int r32, int hi) {
;   p0 = f32x16{}; p1 = f32x16{};
; #pragma unroll
;   for (int d0 = 0; d0 < ND0; ++d0) { int cb = (d0 * 16 + hi * 8) * 2;
;     bf16x8 b0 = *reinterpret_cast<const bf16x8*>(Ks + KSWZ(r32, cb));
;     bf16x8 b1 = *reinterpret_cast<const bf16x8*>(Ks + KSWZ(32 + r32, cb));
;     p0 = __builtin_amdgcn_mfma_f32_32x32x16_bf16(b0, qr[d0], p0, 0, 0, 0);
;     p1 = __builtin_amdgcn_mfma_f32_32x32x16_bf16(b1, qr[d0], p1, 0, 0, 0); }
; }
; template <int ND0, int LDQ, int LDK, int LDO> ...
;     ...
;     SBAR(); qkt<ND0>(pA0, pA1, Kq0, qr, r32, hi);
;     finishSM(pB0, pB1, alB, l_reg, pa0, pa1, pa2, pa3); SBAR();
;     if (j + 3 < NT) SLOAD_A((j + 3) * KVBLK); SBAR();
.LBB0_153:
	v_mov_b32_e32 v242, 0x800
	v_exp_f32_e32 v245, v88
	v_exp_f32_e32 v246, v89
	s_waitcnt lgkmcnt(0)
	v_mfma_f32_32x32x16_bf16 v[96:111], v[64:67], v[114:117], 0
	v_exp_f32_e32 v247, v90
	v_exp_f32_e32 v231, v91
	v_exp_f32_e32 v243, v92
	v_exp_f32_e32 v252, v93
	v_exp_f32_e32 v253, v94
	v_exp_f32_e32 v95, v95
	v_mfma_f32_32x32x16_bf16 v[64:79], v[68:71], v[114:117], 0
	ds_read_b128 v[238:241], v200 offset:32768
	ds_read_b128 v[234:237], v200 offset:40960
	s_waitcnt lgkmcnt(0)
	v_mfma_f32_32x32x16_bf16 v[96:111], v[238:241], v[122:125], v[96:111]
	v_mfma_f32_32x32x16_bf16 v[64:79], v[234:237], v[122:125], v[64:79]
	ds_read_b128 v[234:237], v202 offset:32768
	ds_read_b128 v[238:241], v202 offset:40960
	s_waitcnt lgkmcnt(0)
	v_mfma_f32_32x32x16_bf16 v[96:111], v[234:237], v[142:145], v[96:111]
	v_mfma_f32_32x32x16_bf16 v[64:79], v[238:241], v[142:145], v[64:79]
	ds_read_b128 v[234:237], v201 offset:32768
	ds_read_b128 v[238:241], v201 offset:40960
	s_waitcnt lgkmcnt(0)
	v_mfma_f32_32x32x16_bf16 v[96:111], v[234:237], v[138:141], v[96:111]
	v_mfma_f32_32x32x16_bf16 v[64:79], v[238:241], v[138:141], v[64:79]
	ds_read_b128 v[234:237], v203 offset:32768
	ds_read_b128 v[238:241], v203 offset:40960
	s_waitcnt lgkmcnt(0)
	v_mfma_f32_32x32x16_bf16 v[96:111], v[234:237], v[134:137], v[96:111]
	v_mfma_f32_32x32x16_bf16 v[64:79], v[238:241], v[134:137], v[64:79]
	ds_read_b128 v[234:237], v204 offset:32768
	ds_read_b128 v[238:241], v204 offset:40960
	s_waitcnt lgkmcnt(0)
	v_mfma_f32_32x32x16_bf16 v[96:111], v[234:237], v[130:133], v[96:111]
	v_mfma_f32_32x32x16_bf16 v[64:79], v[238:241], v[130:133], v[64:79]
	ds_read_b128 v[234:237], v206 offset:32768
	ds_read_b128 v[238:241], v206 offset:40960
	s_waitcnt lgkmcnt(0)
	v_mfma_f32_32x32x16_bf16 v[96:111], v[234:237], v[126:129], v[96:111]
	v_mfma_f32_32x32x16_bf16 v[64:79], v[238:241], v[126:129], v[64:79]
	ds_read_b128 v[234:237], v205 offset:32768
	ds_read_b128 v[238:241], v205 offset:40960
	s_waitcnt lgkmcnt(0)
	v_mfma_f32_32x32x16_bf16 v[96:111], v[234:237], v[118:121], v[96:111]
	v_exp_f32_e32 v234, v80
	v_add_f32_e32 v80, v244, v226
	v_add_f32_e32 v80, v224, v80
	v_add_f32_e32 v80, v227, v80
	v_add_f32_e32 v80, v223, v80
	v_add_f32_e32 v80, v225, v80
	v_add_f32_e32 v80, v221, v80
	v_add_f32_e32 v80, v222, v80
	v_add_f32_e32 v80, v218, v80
	v_add_f32_e32 v80, v220, v80
	v_add_f32_e32 v80, v217, v80
	v_add_f32_e32 v80, v219, v80
	v_add_f32_e32 v80, v214, v80
	v_exp_f32_e32 v235, v81
	v_add_f32_e32 v80, v216, v80
	v_exp_f32_e32 v236, v82
	v_add_f32_e32 v80, v213, v80
	v_exp_f32_e32 v237, v83
	v_add_f32_e32 v80, v215, v80
	v_mfma_f32_32x32x16_bf16 v[64:79], v[238:241], v[118:121], v[64:79]
	v_exp_f32_e32 v238, v84
	v_add_f32_e32 v80, v234, v80
	v_exp_f32_e32 v239, v85
	v_add_f32_e32 v80, v235, v80
	v_exp_f32_e32 v240, v86
	v_add_f32_e32 v80, v236, v80
	v_exp_f32_e32 v241, v87
	v_add_f32_e32 v80, v237, v80
	v_add_f32_e32 v80, v238, v80
	v_add_f32_e32 v80, v239, v80
	v_add_f32_e32 v80, v240, v80
	v_add_f32_e32 v80, v241, v80
	v_add_f32_e32 v80, v245, v80
	v_add_f32_e32 v80, v246, v80
	v_add_f32_e32 v80, v247, v80
	v_add_f32_e32 v80, v231, v80
	v_add_f32_e32 v80, v243, v80
	v_add_f32_e32 v80, v252, v80
	v_add_f32_e32 v80, v253, v80
	v_add_f32_e32 v211, v95, v80
	v_mov_b32_e32 v212, v211
	v_cvt_pk_bf16_f32 v80, v226, v244
	v_cvt_pk_bf16_f32 v81, v224, v227
	v_cvt_pk_bf16_f32 v82, v223, v225
	v_cvt_pk_bf16_f32 v83, v221, v222
	v_cvt_pk_bf16_f32 v84, v218, v220
	v_cvt_pk_bf16_f32 v85, v217, v219
	v_cvt_pk_bf16_f32 v86, v214, v216
	v_cvt_pk_bf16_f32 v87, v213, v215
	v_cvt_pk_bf16_f32 v88, v234, v235
	v_cvt_pk_bf16_f32 v89, v236, v237
	v_cvt_pk_bf16_f32 v90, v238, v239
	v_cvt_pk_bf16_f32 v91, v240, v241
	v_cvt_pk_bf16_f32 v92, v245, v246
	v_cvt_pk_bf16_f32 v93, v247, v231
	v_cvt_pk_bf16_f32 v94, v243, v252
	v_cvt_pk_bf16_f32 v95, v253, v95
	v_permlane32_swap_b32_e32 v211, v212
	v_permlane32_swap_b32_e32 v80, v82
	v_permlane32_swap_b32_e32 v81, v83
	v_permlane32_swap_b32_e32 v84, v86
	v_permlane32_swap_b32_e32 v85, v87
	v_permlane32_swap_b32_e32 v88, v90
	v_permlane32_swap_b32_e32 v89, v91
	v_permlane32_swap_b32_e32 v92, v94
	v_permlane32_swap_b32_e32 v93, v95
	s_add_i32 s39, s39, 2
	s_cmp_ge_u32 s39, s38
	s_cselect_b64 s[4:5], -1, 0
	s_and_b64 vcc, exec, s[4:5]
	s_cbranch_vccnz .Lgqa_pf_skip
	v_add_co_u32_e32 v146, vcc, 0xfffe8000, v188
	s_nop 1
	v_addc_co_u32_e32 v147, vcc, -1, v189, vcc
	global_load_dwordx4 v[158:161], v[146:147], off
	global_load_dwordx4 v[150:153], v[146:147], off offset:-512
	global_load_dwordx4 v[154:157], v[188:189], off
	global_load_dwordx4 v[146:149], v[188:189], off offset:-512

; #define SBAR() __builtin_amdgcn_sched_barrier(0)
; #define KWRITE(b, src0, src1) do { if constexpr (ND0 == 4) { *(bf16x8*)(K_lds + (b) * SHM_K + KSWZ(kr, kcb)) = src0; } \
;     else { int kc = sc * 2; *(bf16x8*)(K_lds + (b) * SHM_K + KSWZ(sr, kc)) = src0; *(bf16x8*)(K_lds + (b) * SHM_K + KSWZ(32 + sr, kc)) = src1; } } while (0)
; #define SLOAD_B(k0) do { vs0b = *reinterpret_cast<const bf16x8*>(&Vh[(long)((k0) + sr) * LDK + sc]); vs1b = *reinterpret_cast<const bf16x8*>(&Vh[(long)((k0) + 32 + sr) * LDK + sc]); KLOAD(ks0b, ks1b, k0); } while (0)
; #define PSM(P0, P1, MN, AL) do { if constexpr (PRE) partialSM_pre(P0, P1, m_reg, AL, 11.541560327111707f); else partialSM(P0, P1, m_reg, MN, AL, C, thr_raw); } while (0)
; __device__ __forceinline__ void finishSM(f32x16& p0, f32x16& p1, float alpha, float& l_reg, bf16x8& pa0, bf16x8& pa1, bf16x8& pa2, bf16x8& pa3) {
; #pragma unroll
;   for (int r = 0; r < 16; ++r) p1[r] = __builtin_amdgcn_exp2f(p1[r]);
;   float ps = 0;
; #pragma unroll
;   for (int r = 0; r < 16; ++r) ps += p0[r];
; #pragma unroll
;   for (int r = 0; r < 16; ++r) ps += p1[r];
;   { auto rr = __builtin_amdgcn_permlane32_swap(__float_as_uint(ps), __float_as_uint(ps), false, false);
;     ps = __uint_as_float(rr[0]) + __uint_as_float(rr[1]); }
;   l_reg = l_reg * alpha + ps;
;     ...
;   PK4(p0, 0, pa0); PK4(p0, 8, pa1); PK4(p1, 0, pa2); PK4(p1, 8, pa3);
;     ...
; }
; template <int ND0>
; __device__ __forceinline__ void qkt(f32x16& p0, f32x16& p1, const char* Ks, const bf16x8* qr, int r32, int hi) {
;   p0 = f32x16{}; p1 = f32x16{};
; #pragma unroll
;   for (int d0 = 0; d0 < ND0; ++d0) { int cb = (d0 * 16 + hi * 8) * 2;
;     bf16x8 b0 = *reinterpret_cast<const bf16x8*>(Ks + KSWZ(r32, cb));
;     bf16x8 b1 = *reinterpret_cast<const bf16x8*>(Ks + KSWZ(32 + r32, cb));
;     p0 = __builtin_amdgcn_mfma_f32_32x32x16_bf16(b0, qr[d0], p0, 0, 0, 0);
;     p1 = __builtin_amdgcn_mfma_f32_32x32x16_bf16(b1, qr[d0], p1, 0, 0, 0); }
; }
; template <int ND0, int LDQ, int LDK, int LDO> ...
;     ...
;     SBAR(); qkt<ND0>(pB0, pB1, Kq1, qr, r32, hi);
;     finishSM(pA0, pA1, alA, l_reg, pa0, pa1, pa2, pa3); SBAR();
;     SLOAD_B((j + 2) * KVBLK); SBAR();
;     pv_d0(o, vb0, pa0, pa1, pa2, pa3); KWRITE(0, ks0a, ks1a); PSM(pB0, pB1, mnB, alB);
.LBB0_214:
	v_exp_f32_e32 v150, v64
	s_waitcnt lgkmcnt(0)
	v_mfma_f32_32x32x16_bf16 v[96:111], v[80:83], v[126:129], 0
	v_add_f32_e32 v64, v206, v176
	v_add_f32_e32 v64, v174, v64
	v_add_f32_e32 v64, v177, v64
	v_add_f32_e32 v64, v152, v64
	v_add_f32_e32 v64, v175, v64
	v_add_f32_e32 v64, v151, v64
	v_add_f32_e32 v64, v153, v64
	v_mfma_f32_32x32x16_bf16 v[80:95], v[84:87], v[126:129], 0
	ds_read_b128 v[202:205], v198 offset:49152
	ds_read_b128 v[208:211], v198 offset:57344
	v_add_f32_e32 v64, v147, v64
	v_add_f32_e32 v64, v149, v64
	v_add_f32_e32 v64, v145, v64
	v_add_f32_e32 v64, v148, v64
	v_add_f32_e32 v64, v143, v64
	v_add_f32_e32 v64, v146, v64
	v_add_f32_e32 v64, v142, v64
	s_waitcnt lgkmcnt(0)
	v_mfma_f32_32x32x16_bf16 v[96:111], v[202:205], v[122:125], v[96:111]
	v_add_f32_e32 v64, v144, v64
	v_exp_f32_e32 v207, v68
	v_add_f32_e32 v64, v150, v64
	v_exp_f32_e32 v212, v73
	v_exp_f32_e32 v213, v74
	v_exp_f32_e32 v214, v75
	v_exp_f32_e32 v215, v76
	v_mfma_f32_32x32x16_bf16 v[80:95], v[208:211], v[122:125], v[80:95]
	ds_read_b128 v[222:225], v199 offset:49152
	ds_read_b128 v[234:237], v199 offset:57344
	v_exp_f32_e32 v216, v77
	v_exp_f32_e32 v217, v78
	v_exp_f32_e32 v79, v79
	s_waitcnt lgkmcnt(0)
	v_mfma_f32_32x32x16_bf16 v[96:111], v[222:225], v[118:121], v[96:111]
	v_mfma_f32_32x32x16_bf16 v[80:95], v[234:237], v[118:121], v[80:95]
	ds_read_b128 v[238:241], v196 offset:49152
	ds_read_b128 v[244:247], v196 offset:57344
	s_waitcnt lgkmcnt(0)
	v_mfma_f32_32x32x16_bf16 v[96:111], v[238:241], v[114:117], v[96:111]
	v_exp_f32_e32 v203, v65
	v_exp_f32_e32 v204, v66
	v_exp_f32_e32 v205, v67
	v_add_f32_e32 v64, v203, v64
	v_add_f32_e32 v64, v204, v64
	v_add_f32_e32 v64, v205, v64
	v_mfma_f32_32x32x16_bf16 v[80:95], v[244:247], v[114:117], v[80:95]
	v_exp_f32_e32 v208, v69
	v_exp_f32_e32 v209, v70
	v_exp_f32_e32 v210, v71
	v_exp_f32_e32 v211, v72
	v_add_f32_e32 v64, v207, v64
	v_add_f32_e32 v64, v208, v64
	v_add_f32_e32 v64, v209, v64
	v_add_f32_e32 v64, v210, v64
	v_add_f32_e32 v64, v211, v64
	v_add_f32_e32 v64, v212, v64
	v_add_f32_e32 v64, v213, v64
	v_add_f32_e32 v64, v214, v64
	v_add_f32_e32 v64, v215, v64
	v_add_f32_e32 v64, v216, v64
	v_add_f32_e32 v64, v217, v64
	v_add_f32_e32 v201, v79, v64
	v_mov_b32_e32 v202, v201
	v_cvt_pk_bf16_f32 v64, v176, v206
	v_cvt_pk_bf16_f32 v65, v174, v177
	v_cvt_pk_bf16_f32 v66, v152, v175
	v_cvt_pk_bf16_f32 v67, v151, v153
	v_cvt_pk_bf16_f32 v68, v147, v149
	v_cvt_pk_bf16_f32 v69, v145, v148
	v_cvt_pk_bf16_f32 v70, v143, v146
	v_cvt_pk_bf16_f32 v71, v142, v144
	v_cvt_pk_bf16_f32 v72, v150, v203
	v_cvt_pk_bf16_f32 v73, v204, v205
	v_cvt_pk_bf16_f32 v74, v207, v208
	v_cvt_pk_bf16_f32 v75, v209, v210
	v_cvt_pk_bf16_f32 v76, v211, v212
	v_cvt_pk_bf16_f32 v77, v213, v214
	v_cvt_pk_bf16_f32 v78, v215, v216
	v_cvt_pk_bf16_f32 v79, v217, v79
	v_permlane32_swap_b32_e32 v201, v202
	v_permlane32_swap_b32_e32 v64, v66
	v_permlane32_swap_b32_e32 v65, v67
	v_permlane32_swap_b32_e32 v68, v70
	v_permlane32_swap_b32_e32 v69, v71
	v_permlane32_swap_b32_e32 v72, v74
	v_permlane32_swap_b32_e32 v73, v75
	v_permlane32_swap_b32_e32 v76, v78
	v_permlane32_swap_b32_e32 v77, v79
	global_load_dwordx4 v[142:145], v[172:173], off
	v_lshl_add_u64 v[174:175], v[172:173], 0, s[34:35]
	global_load_dwordx4 v[146:149], v[174:175], off
	global_load_dwordx4 v[150:153], v[170:171], off offset:2048
	v_lshl_add_u64 v[172:173], v[172:173], 0, s[46:47]
	v_lshl_add_u64 v[170:171], v[170:171], 0, s[46:47]
	v_cmp_neq_f32_e32 vcc, 0, v191
	ds_read_b64_tr_b16 v[204:205], v192 offset:0
	ds_read_b64_tr_b16 v[206:207], v192 offset:0x800
	ds_read_b64_tr_b16 v[208:209], v192 offset:0x1000
	ds_read_b64_tr_b16 v[210:211], v192 offset:0x1800
	ds_read_b64_tr_b16 v[212:213], v192 offset:0x2000
	ds_read_b64_tr_b16 v[214:215], v192 offset:0x2800
	ds_read_b64_tr_b16 v[216:217], v192 offset:0x3000
	ds_read_b64_tr_b16 v[218:219], v192 offset:0x3800
	s_cbranch_vccnz .LBB0_230

; #define SBAR() __builtin_amdgcn_sched_barrier(0)
; #define SLOAD_A(k0) do { vs0a = *reinterpret_cast<const bf16x8*>(&Vh[(long)((k0) + sr) * LDK + sc]); vs1a = *reinterpret_cast<const bf16x8*>(&Vh[(long)((k0) + 32 + sr) * LDK + sc]); KLOAD(ks0a, ks1a, k0); } while (0)
; __device__ __forceinline__ void finishSM(f32x16& p0, f32x16& p1, float alpha, float& l_reg, bf16x8& pa0, bf16x8& pa1, bf16x8& pa2, bf16x8& pa3) {
; #pragma unroll
;   for (int r = 0; r < 16; ++r) p1[r] = __builtin_amdgcn_exp2f(p1[r]);
;   float ps = 0;
; #pragma unroll
;   for (int r = 0; r < 16; ++r) ps += p0[r];
; #pragma unroll
;   for (int r = 0; r < 16; ++r) ps += p1[r];
;   { auto rr = __builtin_amdgcn_permlane32_swap(__float_as_uint(ps), __float_as_uint(ps), false, false);
;     ps = __uint_as_float(rr[0]) + __uint_as_float(rr[1]); }
;   l_reg = l_reg * alpha + ps;
;     ...
;   PK4(p0, 0, pa0); PK4(p0, 8, pa1); PK4(p1, 0, pa2); PK4(p1, 8, pa3);
;     ...
; }
; template <int ND0>
; __device__ __forceinline__ void qkt(f32x16& p0, f32x16& p1, const char* Ks, const bf16x8* qr, int r32, int hi) {
;   p0 = f32x16{}; p1 = f32x16{};
; #pragma unroll
;   for (int d0 = 0; d0 < ND0; ++d0) { int cb = (d0 * 16 + hi * 8) * 2;
;     bf16x8 b0 = *reinterpret_cast<const bf16x8*>(Ks + KSWZ(r32, cb));
;     bf16x8 b1 = *reinterpret_cast<const bf16x8*>(Ks + KSWZ(32 + r32, cb));
;     p0 = __builtin_amdgcn_mfma_f32_32x32x16_bf16(b0, qr[d0], p0, 0, 0, 0);
;     p1 = __builtin_amdgcn_mfma_f32_32x32x16_bf16(b1, qr[d0], p1, 0, 0, 0); }
; }
; template <int ND0, int LDQ, int LDK, int LDO> ...
;     ...
;     SBAR(); qkt<ND0>(pA0, pA1, Kq0, qr, r32, hi);
;     finishSM(pB0, pB1, alB, l_reg, pa0, pa1, pa2, pa3); SBAR();
;     if (j + 3 < NT) SLOAD_A((j + 3) * KVBLK); SBAR();
.LBB0_220:
	v_exp_f32_e32 v226, v84
	v_exp_f32_e32 v227, v85
	s_waitcnt lgkmcnt(0)
	v_mfma_f32_32x32x16_bf16 v[96:111], v[64:67], v[126:129], 0
	v_exp_f32_e32 v234, v86
	v_exp_f32_e32 v235, v87
	v_exp_f32_e32 v236, v88
	v_exp_f32_e32 v237, v89
	v_exp_f32_e32 v238, v90
	v_exp_f32_e32 v239, v91
	v_exp_f32_e32 v240, v92
	v_mfma_f32_32x32x16_bf16 v[64:79], v[68:71], v[126:129], 0
	ds_read_b128 v[222:225], v198 offset:32768
	ds_read_b128 v[244:247], v198 offset:40960
	v_exp_f32_e32 v241, v93
	v_exp_f32_e32 v95, v95
	s_waitcnt lgkmcnt(0)
	v_mfma_f32_32x32x16_bf16 v[96:111], v[222:225], v[122:125], v[96:111]
	v_mfma_f32_32x32x16_bf16 v[64:79], v[244:247], v[122:125], v[64:79]
	ds_read_b128 v[130:133], v199 offset:32768
	ds_read_b128 v[134:137], v199 offset:40960
	s_waitcnt lgkmcnt(0)
	v_mfma_f32_32x32x16_bf16 v[96:111], v[130:133], v[118:121], v[96:111]
	v_mfma_f32_32x32x16_bf16 v[64:79], v[134:137], v[118:121], v[64:79]
	ds_read_b128 v[138:141], v196 offset:32768
	ds_read_b128 v[244:247], v196 offset:40960
	s_waitcnt lgkmcnt(0)
	v_mfma_f32_32x32x16_bf16 v[96:111], v[138:141], v[114:117], v[96:111]
	v_exp_f32_e32 v222, v80
	v_add_f32_e32 v80, v221, v219
	v_add_f32_e32 v80, v217, v80
	v_add_f32_e32 v80, v220, v80
	v_add_f32_e32 v80, v215, v80
	v_add_f32_e32 v80, v218, v80
	v_add_f32_e32 v80, v214, v80
	v_add_f32_e32 v80, v216, v80
	v_add_f32_e32 v80, v211, v80
	v_add_f32_e32 v80, v213, v80
	v_add_f32_e32 v80, v209, v80
	v_add_f32_e32 v80, v212, v80
	v_add_f32_e32 v80, v207, v80
	v_exp_f32_e32 v223, v81
	v_add_f32_e32 v80, v210, v80
	v_exp_f32_e32 v224, v82
	v_add_f32_e32 v80, v206, v80
	v_exp_f32_e32 v225, v83
	v_add_f32_e32 v80, v208, v80
	v_add_f32_e32 v80, v222, v80
	v_add_f32_e32 v80, v223, v80
	v_add_f32_e32 v80, v224, v80
	v_add_f32_e32 v80, v225, v80
	v_add_f32_e32 v80, v226, v80
	v_add_f32_e32 v80, v227, v80
	v_add_f32_e32 v80, v234, v80
	v_add_f32_e32 v80, v235, v80
	v_add_f32_e32 v80, v236, v80
	v_add_f32_e32 v80, v237, v80
	v_mfma_f32_32x32x16_bf16 v[64:79], v[244:247], v[114:117], v[64:79]
	v_exp_f32_e32 v244, v94
	v_add_f32_e32 v80, v238, v80
	v_add_f32_e32 v80, v239, v80
	v_add_f32_e32 v80, v240, v80
	v_add_f32_e32 v80, v241, v80
	v_add_f32_e32 v80, v244, v80
	v_add_f32_e32 v204, v95, v80
	v_mov_b32_e32 v205, v204
	v_cvt_pk_bf16_f32 v80, v219, v221
	v_cvt_pk_bf16_f32 v81, v217, v220
	v_cvt_pk_bf16_f32 v82, v215, v218
	v_cvt_pk_bf16_f32 v83, v214, v216
	v_cvt_pk_bf16_f32 v84, v211, v213
	v_cvt_pk_bf16_f32 v85, v209, v212
	v_cvt_pk_bf16_f32 v86, v207, v210
	v_cvt_pk_bf16_f32 v87, v206, v208
	v_cvt_pk_bf16_f32 v88, v222, v223
	v_cvt_pk_bf16_f32 v89, v224, v225
	v_cvt_pk_bf16_f32 v90, v226, v227
	v_cvt_pk_bf16_f32 v91, v234, v235
	v_cvt_pk_bf16_f32 v92, v236, v237
	v_cvt_pk_bf16_f32 v93, v238, v239
	v_cvt_pk_bf16_f32 v94, v240, v241
	v_cvt_pk_bf16_f32 v95, v244, v95
	v_permlane32_swap_b32_e32 v204, v205
	v_permlane32_swap_b32_e32 v80, v82
	v_permlane32_swap_b32_e32 v81, v83
	v_permlane32_swap_b32_e32 v84, v86
	v_permlane32_swap_b32_e32 v85, v87
	v_permlane32_swap_b32_e32 v88, v90
	v_permlane32_swap_b32_e32 v89, v91
	v_permlane32_swap_b32_e32 v92, v94
	v_permlane32_swap_b32_e32 v93, v95
	s_cmp_ge_u32 s40, s39
	s_cselect_b64 s[18:19], -1, 0
	s_and_b64 vcc, exec, s[18:19]
	s_cbranch_vccnz .Ldiff_pf_skip
	global_load_dwordx4 v[130:133], v[172:173], off
	v_lshl_add_u64 v[174:175], v[172:173], 0, s[34:35]
	global_load_dwordx4 v[134:137], v[174:175], off
	global_load_dwordx4 v[138:141], v[170:171], off offset:2048
	v_lshl_add_u64 v[172:173], v[172:173], 0, s[46:47]
	v_lshl_add_u64 v[170:171], v[170:171], 0, s[46:47]
